# barrier: speculative early L2 write-back by the arrivers with nloc/2 and nloc/8 blocks still outstanding
# baseline (speedup 1.0000x reference)
.Lxb_spin_1:
	v_sub_u32_e32 v13, v10, v8
	v_lshrrev_b32_e32 v14, 1, v4
	v_lshrrev_b32_e32 v15, 3, v4
	v_cmp_eq_u32_e32 vcc, v13, v14
	s_cbranch_vccnz .Lxb_swb_1
	v_cmp_eq_u32_e32 vcc, v13, v15
	s_cbranch_vccz .Lxb_nswb_1
.Lxb_swb_1:
	buffer_wbl2 sc1
